# z128 activation loads batched (8 loads, counted waits) - cumulative: epilogue/streaming-phase de-serialisation
# speedup vs baseline: 1.0029x; 1.0029x over previous
; __device__ __forceinline__ unsigned cvt_pk_bf16(float lo, float hi) { unsigned r; asm("v_cvt_pk_bf16_f32 %0, %1, %2" : "=v"(r) : "v"(lo), "v"(hi)); return r; }
; __device__ __forceinline__ int obid() { extern __shared__ __attribute__((aligned(16))) unsigned char shm_vb[]; return __builtin_amdgcn_readfirstlane(*(volatile LAS int*)((LAS unsigned char*)shm_vb + VB_OFF)); }
; __device__ __forceinline__ float rinv_of(unsigned long long ss) { return rsqrtf((float)ss * (1.f / 16777216.f) * (1.f / DM) + 1e-6f); }
; __device__ __forceinline__ void phase_z128(const bf16_t* __restrict__ xb, const bf16_t* __restrict__ w128, const unsigned long long* __restrict__ ss, bf16_t* __restrict__ zt, LAS float* red) {
;     ...
;   for (int task = obid(); task < TS / 16; task += gridDim.x) {
;     const int t0 = task * 16;
;     const bf16_t* ap = xb + (size_t)(t0 + (lane & 15)) * DM + 8 * (lane >> 4) + wid * 256;
;     const bf16_t* bp = w128 + (size_t)(lane & 15) * DM + 8 * (lane >> 4) + wid * 256;
;     f32x4 acc = {0.f, 0.f, 0.f, 0.f};
; #pragma unroll
;     for (int ch = 0; ch < 8; ++ch) {
;       const bf16x8 av = *(const bf16x8*)(ap + ch * 32), bv = *(const bf16x8*)(bp + ch * 32);
;       acc = __builtin_amdgcn_mfma_f32_16x16x32_bf16(av, bv, acc, 0, 0, 0);
;     }
;     __syncthreads();
; #pragma unroll
;     for (int r = 0; r < 4; ++r) red[(wid * 4 + r) * 64 + lane] = acc[r];
;     __syncthreads();
;     if (tid < 256) {
;       const int r = tid >> 6, l = tid & 63;
;       float s = 0.f;
; #pragma unroll
;       for (int w = 0; w < 8; ++w) s += red[(w * 4 + r) * 64 + l];
;       const int t = t0 + (l >> 4) * 4 + r;
;       zt[(size_t)(2048 + (l & 15)) * TS + t] = (bf16_t)(cvt_pk_bf16(s * rinv_of(ss[t]), 0.f) & 0xffffu);
;     }
;   }
.LBB0_265:
	v_add_u32_e32 v40, s1, v36
	v_ashrrev_i32_e32 v41, 31, v40
	v_lshlrev_b64 v[40:41], 12, v[40:41]
	v_lshl_add_u64 v[48:49], v[32:33], 0, v[40:41]
	global_load_dwordx4 v[64:67], v[48:49], off
	global_load_dwordx4 v[68:71], v[48:49], off offset:64
	global_load_dwordx4 v[72:75], v[48:49], off offset:128
	global_load_dwordx4 v[76:79], v[48:49], off offset:192
	global_load_dwordx4 v[84:87], v[48:49], off offset:256
	global_load_dwordx4 v[88:91], v[48:49], off offset:320
	global_load_dwordx4 v[92:95], v[48:49], off offset:384
	global_load_dwordx4 v[96:99], v[48:49], off offset:448
	s_waitcnt vmcnt(7)
	v_mfma_f32_16x16x32_bf16 v[40:43], v[64:67], v[24:27], 0
	s_waitcnt vmcnt(6)
	v_mfma_f32_16x16x32_bf16 v[40:43], v[68:71], v[0:3], v[40:43]
	s_waitcnt vmcnt(5)
	v_mfma_f32_16x16x32_bf16 v[40:43], v[72:75], v[4:7], v[40:43]
	s_waitcnt vmcnt(4)
	v_mfma_f32_16x16x32_bf16 v[40:43], v[76:79], v[8:11], v[40:43]
	s_waitcnt vmcnt(3)
	v_mfma_f32_16x16x32_bf16 v[40:43], v[84:87], v[12:15], v[40:43]
	s_waitcnt vmcnt(2)
	v_mfma_f32_16x16x32_bf16 v[40:43], v[88:91], v[16:19], v[40:43]
	s_waitcnt vmcnt(1)
	v_mfma_f32_16x16x32_bf16 v[40:43], v[92:95], v[20:23], v[40:43]
	s_waitcnt lgkmcnt(0)
	s_barrier
	s_waitcnt vmcnt(0)
	v_mfma_f32_16x16x32_bf16 v[40:43], v[96:99], v[28:31], v[40:43]
	s_nop 7
	ds_write2st64_b32 v39, v40, v41 offset1:1
	ds_write2st64_b32 v39, v42, v43 offset0:2 offset1:3
	s_waitcnt lgkmcnt(0)
	s_barrier
	s_and_saveexec_b64 s[6:7], vcc
	s_cbranch_execz .LBB0_264
	ds_read2st64_b32 v[40:41], v37 offset1:4
	s_waitcnt lgkmcnt(0)
	v_add_f32_e32 v40, 0, v40
	v_add_f32_e32 v42, v40, v41
	ds_read2st64_b32 v[40:41], v37 offset0:8 offset1:12
	s_waitcnt lgkmcnt(0)
	v_add_f32_e32 v40, v42, v40
	v_add_f32_e32 v42, v40, v41
	ds_read2st64_b32 v[40:41], v37 offset0:16 offset1:20
	s_waitcnt lgkmcnt(0)
	v_add_f32_e32 v40, v42, v40
	v_add_f32_e32 v42, v40, v41
	ds_read2st64_b32 v[40:41], v37 offset0:24 offset1:28
	s_waitcnt lgkmcnt(0)
	v_add_f32_e32 v40, v42, v40
	v_add_f32_e32 v44, v40, v41
	v_add_u32_e32 v40, s1, v38
	v_ashrrev_i32_e32 v41, 31, v40
	v_lshl_add_u64 v[42:43], v[40:41], 3, s[4:5]
	global_load_dwordx2 v[42:43], v[42:43], off
	v_lshl_add_u64 v[40:41], v[40:41], 1, v[34:35]
	s_waitcnt vmcnt(0) lgkmcnt(0)
	v_ffbh_u32_e32 v45, v43
	v_min_u32_e32 v45, 32, v45
	v_lshlrev_b64 v[42:43], v45, v[42:43]
	v_min_u32_e32 v42, 1, v42
	v_or_b32_e32 v42, v43, v42
	v_cvt_f32_u32_e32 v42, v42
	v_sub_u32_e32 v43, 32, v45
	v_ldexp_f32 v42, v42, v43
	v_mul_f32_e32 v42, 0x33800000, v42
	v_fmamk_f32 v42, v42, 0x3a000000, v234
	v_cmp_gt_f32_e64 s[2:3], s50, v42
	v_mul_f32_e32 v43, 0x4b800000, v42
	s_nop 0
	v_cndmask_b32_e64 v42, v42, v43, s[2:3]
	v_rsq_f32_e32 v42, v42
	s_nop 0
	v_mul_f32_e32 v43, 0x45800000, v42
	v_cndmask_b32_e64 v42, v42, v43, s[2:3]
	v_mul_f32_e32 v42, v44, v42
	v_cvt_pk_bf16_f32 v42, v42, v81
	global_store_short v[40:41], v42, off
	s_branch .LBB0_264
